# hg_out: per-unit 128x128 bf16 state staged once per workgroup into LDS by 4 LDS-DMA loads per wave (XOR-swizzled source), fragments read with ds_read_b128 instead of 16 row-strided global dwordx4 load
# speedup vs baseline: 1.0171x; 1.0099x over previous
; DI void hg_out_units(LAS unsigned char* L, int u0, int G, const float* LOGF, const bf16* QHG, const bf16* IHG, const bf16* GHG, const bf16* ST, const float* og, bf16* MIX, int tid, int wave, int lane) {
;     ...
;     const int c = tid & 127, seg = tid >> 7;
;     const int lr = lane & 15, quad = lane >> 4, tt = wave >> 1, dh = wave & 1;
;     int unit = u0; if (unit >= 2048) return;
;     float g[16]; bf16 qraw[16]; bf16x8 v8[2];
;     ...
;     HGO_LOAD(unit);
.LBB0_332:
	s_or_b64 exec, exec, s[0:1]
	s_mov_b32 s0, -1
	s_waitcnt lgkmcnt(0)
	s_barrier
	s_mov_b64 s[24:25], 0
	v_mbcnt_lo_u32_b32 v0, s0, 0
	v_mbcnt_hi_u32_b32 v0, s0, v0
	v_add_u32_e32 v8, s68, v0
	s_and_b64 vcc, exec, s[4:5]
	v_readfirstlane_b32 s0, v8
	s_cbranch_vccnz .LBB0_352
	v_readlane_b32 s4, v252, 0
	v_mov_b64_e32 v[0:1], s[24:25]
	v_readlane_b32 s5, v252, 1
	v_readlane_b32 s6, v252, 2
	v_readlane_b32 s7, v252, 3
	s_mov_b64 s[4:5], 0x1b000000
	s_lshl_b32 s36, s46, 7
	v_lshl_add_u64 v[84:85], s[6:7], 0, v[0:1]
	v_lshl_add_u64 v[86:87], v[84:85], 0, s[4:5]
	s_mov_b64 s[4:5], 0x11000000
	v_lshl_add_u64 v[88:89], v[84:85], 0, s[4:5]
	s_mov_b64 s[4:5], 0x19000000
	v_readlane_b32 s8, v252, 39
	v_lshl_add_u64 v[90:91], v[84:85], 0, s[4:5]
	s_lshl_b64 s[4:5], s[36:37], 2
	v_readlane_b32 s10, v252, 41
	v_readlane_b32 s11, v252, 42
	s_add_u32 s68, s10, s4
	s_addc_u32 s69, s11, s5
	s_mov_b64 s[4:5], 0x17000000
	v_ashrrev_i32_e32 v23, 7, v8
	v_lshl_add_u64 v[10:11], v[84:85], 0, s[4:5]
	v_lshlrev_b32_e32 v92, 4, v23
	v_readlane_b32 s4, v253, 21
	v_ashrrev_i32_e32 v93, 31, v92
	v_readlane_b32 s5, v253, 22
	s_waitcnt vmcnt(3)
	v_and_b32_e32 v128, 0x7f, v8
	v_readlane_b32 s6, v253, 24
	v_lshl_add_u64 v[0:1], s[4:5], 0, v[92:93]
	v_lshlrev_b64 v[0:1], 10, v[0:1]
	v_or3_b32 v0, v128, s6, v0
	v_lshl_add_u64 v[2:3], v[0:1], 2, v[86:87]
	v_or_b32_e32 v6, 0x400, v0
	v_mov_b32_e32 v7, v1
	v_or_b32_e32 v14, 0x800, v0
	v_mov_b32_e32 v15, v1
	v_or_b32_e32 v18, 0xc00, v0
	v_mov_b32_e32 v19, v1
	v_lshl_add_u64 v[4:5], v[0:1], 1, v[88:89]
	v_lshl_add_u64 v[12:13], v[6:7], 2, v[86:87]
	v_lshl_add_u64 v[6:7], v[6:7], 1, v[88:89]
	v_lshl_add_u64 v[16:17], v[14:15], 2, v[86:87]
	v_lshl_add_u64 v[14:15], v[14:15], 1, v[88:89]
	v_lshl_add_u64 v[20:21], v[18:19], 2, v[86:87]
	v_lshl_add_u64 v[18:19], v[18:19], 1, v[88:89]
	global_load_dword v129, v[2:3], off
	global_load_ushort v130, v[4:5], off
	global_load_dword v131, v[12:13], off
	global_load_ushort v132, v[6:7], off
	global_load_dword v133, v[16:17], off
	global_load_ushort v134, v[14:15], off
	global_load_dword v135, v[20:21], off
	global_load_ushort v136, v[18:19], off
	v_or_b32_e32 v2, 0x1000, v0
	v_mov_b32_e32 v3, v1
	v_lshl_add_u64 v[4:5], v[2:3], 2, v[86:87]
	v_lshl_add_u64 v[2:3], v[2:3], 1, v[88:89]
	v_or_b32_e32 v6, 0x1400, v0
	v_mov_b32_e32 v7, v1
	v_or_b32_e32 v14, 0x1800, v0
	v_mov_b32_e32 v15, v1
	v_or_b32_e32 v18, 0x1c00, v0
	v_mov_b32_e32 v19, v1
	v_lshl_add_u64 v[12:13], v[6:7], 2, v[86:87]
	v_lshl_add_u64 v[6:7], v[6:7], 1, v[88:89]
	v_lshl_add_u64 v[16:17], v[14:15], 2, v[86:87]
	v_lshl_add_u64 v[14:15], v[14:15], 1, v[88:89]
	v_lshl_add_u64 v[20:21], v[18:19], 2, v[86:87]
	v_lshl_add_u64 v[18:19], v[18:19], 1, v[88:89]
	global_load_dword v137, v[4:5], off
	global_load_ushort v138, v[2:3], off
	global_load_dword v139, v[12:13], off
	global_load_ushort v140, v[6:7], off
	global_load_dword v142, v[16:17], off
	global_load_ushort v144, v[14:15], off
	global_load_dword v148, v[20:21], off
	global_load_ushort v150, v[18:19], off
	v_or_b32_e32 v2, 0x2000, v0
	v_mov_b32_e32 v3, v1
	v_lshl_add_u64 v[4:5], v[2:3], 2, v[86:87]
	v_lshl_add_u64 v[2:3], v[2:3], 1, v[88:89]
	v_or_b32_e32 v6, 0x2400, v0
	v_mov_b32_e32 v7, v1
	v_or_b32_e32 v14, 0x2800, v0
	v_mov_b32_e32 v15, v1
	v_or_b32_e32 v18, 0x2c00, v0
	v_mov_b32_e32 v19, v1
	v_lshl_add_u64 v[12:13], v[6:7], 2, v[86:87]
	v_lshl_add_u64 v[6:7], v[6:7], 1, v[88:89]
	v_lshl_add_u64 v[16:17], v[14:15], 2, v[86:87]
	v_lshl_add_u64 v[14:15], v[14:15], 1, v[88:89]
	v_lshl_add_u64 v[20:21], v[18:19], 2, v[86:87]
	v_lshl_add_u64 v[18:19], v[18:19], 1, v[88:89]
	global_load_dword v152, v[4:5], off
	global_load_ushort v153, v[2:3], off
	global_load_dword v154, v[12:13], off
	global_load_ushort v155, v[6:7], off
	global_load_dword v156, v[16:17], off
	global_load_ushort v170, v[14:15], off
	global_load_dword v173, v[20:21], off
	global_load_ushort v174, v[18:19], off
	v_or_b32_e32 v2, 0x3000, v0
	v_mov_b32_e32 v3, v1
	v_lshl_add_u64 v[4:5], v[2:3], 2, v[86:87]
	v_or_b32_e32 v6, 0x3400, v0
	v_mov_b32_e32 v7, v1
	v_or_b32_e32 v14, 0x3800, v0
	v_mov_b32_e32 v15, v1
	v_or_b32_e32 v0, 0x3c00, v0
	v_lshl_add_u64 v[2:3], v[2:3], 1, v[88:89]
	v_lshl_add_u64 v[12:13], v[6:7], 2, v[86:87]
	v_lshl_add_u64 v[6:7], v[6:7], 1, v[88:89]
	v_lshl_add_u64 v[16:17], v[14:15], 2, v[86:87]
	v_lshl_add_u64 v[14:15], v[14:15], 1, v[88:89]
	v_lshl_add_u64 v[18:19], v[0:1], 2, v[86:87]
	v_lshl_add_u64 v[0:1], v[0:1], 1, v[88:89]
	global_load_dword v175, v[4:5], off
	global_load_ushort v176, v[2:3], off
	global_load_dword v177, v[12:13], off
	global_load_ushort v178, v[6:7], off
	global_load_dword v179, v[16:17], off
	global_load_ushort v180, v[14:15], off
	global_load_dword v181, v[18:19], off
	global_load_ushort v182, v[0:1], off
	v_add_u32_e32 v4, 0x200, v8
	v_ashrrev_i32_e32 v94, 4, v8
	v_ashrrev_i32_e32 v96, 4, v4
	s_lshl_b32 s36, s6, 1
	v_lshlrev_b32_e32 v2, 4, v8
	v_ashrrev_i32_e32 v95, 31, v94
	v_ashrrev_i32_e32 v97, 31, v96
	v_lshl_add_u64 v[0:1], v[10:11], 0, s[36:37]
	v_and_b32_e32 v160, 0xf0, v2
	v_lshl_add_u64 v[2:3], s[4:5], 0, v[94:95]
	v_lshl_add_u64 v[4:5], s[4:5], 0, v[96:97]
	v_lshl_add_u64 v[0:1], v[0:1], 0, v[160:161]
	v_lshlrev_b64 v[2:3], 11, v[2:3]
; DI void hg_out_units(LAS unsigned char* L, int u0, int G, const float* LOGF, const bf16* QHG, const bf16* IHG, const bf16* GHG, const bf16* ST, const float* og, bf16* MIX, int tid, int wave, int lane) {
;     ...
;     const bf16* stp = ST + (size_t)unit * 16384;
;     bf16x8 stf[4][4]; u32x2 gtv[4];
; #pragma unroll
;     for (int d = 0; d < 4; ++d) { const int dt = 4 * dh + d;
; #pragma unroll
;         for (int ks = 0; ks < 4; ++ks) stf[d][ks] = *(const bf16x8*)(stp + (size_t)(16 * dt + lr) * 128 + 32 * ks + quad * 8);
	v_lshlrev_b64 v[4:5], 11, v[4:5]
	v_lshl_add_u64 v[2:3], v[0:1], 0, v[2:3]
	v_lshl_add_u64 v[4:5], v[0:1], 0, v[4:5]
	global_load_dwordx4 v[0:3], v[2:3], off
	s_nop 0
	global_load_dwordx4 v[4:7], v[4:5], off
	v_readlane_b32 s22, v252, 53
	s_ashr_i32 s1, s0, 6
	s_ashr_i32 s22, s0, 7
	v_readlane_b32 s23, v252, 54
	v_and_b32_e32 v22, 15, v8
	s_and_b32 s74, s1, 1
	s_lshl_b32 s100, s1, 10
	s_add_i32 s100, s100, 0x15000
	v_lshrrev_b32_e32 v230, 4, v8
	v_and_b32_e32 v231, 15, v230
	v_xor_b32_e32 v231, v22, v231
	v_lshlrev_b32_e32 v230, 8, v230
	v_lshl_add_u32 v230, v231, 4, v230
	v_and_b32_e32 v231, 48, v8
	v_sub_u32_e32 v224, v230, v231
	v_add_u32_e32 v224, 0x7000000, v224
	v_mov_b32_e32 v225, 0
	s_lshl_b32 s98, s74, 14
	s_add_i32 s98, s98, 0x15000
	v_lshl_add_u32 v230, v22, 8, s98
	v_bfe_u32 v231, v8, 4, 2
	v_xor_b32_e32 v232, v231, v22
	v_lshl_add_u32 v226, v232, 4, v230
	v_or_b32_e32 v232, 4, v231
	v_xor_b32_e32 v232, v232, v22
	v_lshl_add_u32 v227, v232, 4, v230
	v_or_b32_e32 v232, 8, v231
	v_xor_b32_e32 v232, v232, v22
	v_lshl_add_u32 v228, v232, 4, v230
	v_or_b32_e32 v232, 12, v231
	v_xor_b32_e32 v232, v232, v22
	v_lshl_add_u32 v229, v232, 4, v230
	s_lshl_b32 s4, s22, 4
	s_lshl_b32 s1, s1, 1
	v_or_b32_e32 v98, s4, v22
	s_and_b32 s23, s1, 2
	s_movk_i32 s1, 0x90
	s_and_b32 s0, s0, 0xffffff80
	s_lshl_b32 s6, s74, 2
	v_mul_lo_u32 v16, v98, s1
	v_readlane_b32 s1, v254, 60
	s_add_i32 s0, s0, 0
	s_add_i32 s0, s0, s6
	v_add_u32_e32 v145, s1, v16
	s_movk_i32 s1, 0x110
	v_and_b32_e32 v9, 63, v8
	v_mul_lo_u32 v17, v98, s1
	s_add_i32 s0, s0, 0x14800
	v_bfe_u32 v24, v8, 4, 2
	s_ashr_i32 s5, s4, 31
	s_add_i32 s4, 0, 0x14000
	v_and_b32_e32 v100, 48, v8
	v_add_u32_e32 v17, 0, v17
	s_lshl_b32 s1, s74, 7
	v_lshl_add_u32 v149, v9, 3, s0
	s_lshl_b32 s36, s74, 6
	s_movk_i32 s0, 0x140
	v_lshlrev_b32_e32 v13, 3, v8
	v_lshlrev_b32_e32 v14, 3, v24
	s_waitcnt vmcnt(34)
	v_lshl_add_u32 v141, v8, 2, s4
	v_add_u32_e32 v147, v17, v100
	v_bfe_u32 v8, v8, 2, 2
	s_add_i32 s1, s1, 0
	s_or_b32 s75, s36, 16
	s_or_b32 s81, s36, 32
	s_or_b32 s84, s36, 48
	v_mul_lo_u32 v17, v94, s0
	v_mul_lo_u32 v18, v96, s0
	s_movk_i32 s0, 0x880
	v_readlane_b32 s14, v252, 45
	v_add_u32_e32 v146, v145, v14
	v_or_b32_e32 v14, v14, v8
	v_and_b32_e32 v8, 24, v13
	v_lshl_add_u64 v[102:103], v[10:11], 0, v[160:161]
	v_mul_lo_u32 v10, v23, s0
	s_cmp_le_i32 s23, s22
	v_add_u32_e32 v13, s1, v8
	v_or_b32_e32 v10, v10, v128
	s_cselect_b64 s[0:1], -1, 0
	s_lshl_b32 s14, s23, 4
	v_lshlrev_b32_e32 v12, 2, v24
	v_lshl_add_u32 v151, v10, 1, 0
	v_or_b32_e32 v10, s14, v22
	s_lshl_b32 s93, s23, 5
	s_or_b32 s80, s23, 1
	v_readlane_b32 s15, v252, 46
	v_readlane_b32 s16, v252, 47
	v_readlane_b32 s17, v252, 48
	v_mul_u32_u24_e32 v19, 0x110, v10
	v_or_b32_e32 v10, s14, v12
	s_cmp_lt_i32 s23, s22
	v_readlane_b32 s20, v252, 51
	v_readlane_b32 s21, v252, 52
	v_cmp_gt_i32_e64 s[14:15], v10, v98
	v_cmp_lt_i32_e64 s[16:17], v10, v98
	v_or_b32_e32 v11, 2, v10
	v_or_b32_e32 v10, 3, v10
	s_cselect_b64 s[34:35], -1, 0
	s_lshl_b32 s22, s80, 4
	v_cmp_gt_i32_e64 s[20:21], v10, v98
	v_or_b32_e32 v10, s22, v22
	v_readlane_b32 s18, v252, 49
	v_readlane_b32 s19, v252, 50
	v_or_b32_e32 v8, s36, v12
	v_mul_u32_u24_e32 v20, 0x110, v10
	v_or_b32_e32 v10, s22, v12
	v_add_u32_e32 v15, 0, v160
	v_cmp_gt_i32_e64 s[18:19], v11, v98
	v_cmp_gt_i32_e64 s[22:23], v10, v98
	v_cmp_lt_i32_e64 s[62:63], v10, v98
	v_or_b32_e32 v11, 2, v10
	v_or_b32_e32 v10, 3, v10
	v_lshlrev_b32_e32 v160, 2, v8
	v_mov_b32_e32 v101, v161
	v_mov_b32_e32 v99, s5
	v_lshl_add_u32 v143, v128, 2, s4
	v_cmp_gt_u32_e64 s[4:5], 16, v9
	v_lshlrev_b32_e32 v9, 3, v98
	v_cmp_gt_i32_e64 s[26:27], v11, v98
	v_cmp_gt_i32_e64 s[28:29], v10, v98
	v_lshl_add_u64 v[104:105], s[68:69], 0, v[160:161]
	s_lshl_b32 s68, s74, 14
	v_lshl_add_u64 v[10:11], s[24:25], 0, v[100:101]
	v_readlane_b32 s24, v254, 30
	v_readlane_b32 s9, v252, 40
	v_readlane_b32 s12, v252, 43
	v_readlane_b32 s13, v252, 44
	v_add_u32_e32 v16, 0, v100
	v_mul_u32_u24_e32 v14, 0x140, v14
	v_lshl_or_b32 v21, v22, 8, s68
	v_readlane_b32 s25, v254, 31
	s_lshl_b32 s74, s84, 1
	v_add_u32_e32 v9, 0, v9
	v_readlane_b32 s84, v254, 36
	v_cmp_lt_i32_e64 s[6:7], 0, v23
	v_cmp_lt_i32_e64 s[8:9], 1, v23
	v_cmp_lt_i32_e64 s[10:11], 2, v23
	v_cmp_lt_i32_e64 s[12:13], 3, v23
	s_lshl_b32 s94, s80, 5
	v_or_b32_e32 v106, 0x7000080, v21
	v_mov_b32_e32 v107, v161
	v_lshl_add_u64 v[108:109], s[24:25], 0, v[10:11]
	v_or_b32_e32 v110, 0x7003080, v21
	v_mov_b32_e32 v111, v161
	v_or_b32_e32 v112, 0x7002080, v21
	v_mov_b32_e32 v113, v161
	v_or_b32_e32 v114, 0x7001080, v21
	v_mov_b32_e32 v115, v161
	v_lshlrev_b32_e32 v160, 1, v12
	s_lshl_b32 s80, s36, 1
	s_lshl_b32 s24, s75, 1
	s_lshl_b32 s68, s81, 1
	v_add_u32_e32 v101, v15, v17
	v_add_u32_e32 v157, v15, v18
	v_add_u32_e32 v158, v16, v19
	v_add_u32_e32 v159, v16, v20
	v_add_u32_e32 v171, v13, v14
	v_add_u32_e32 v172, 0x14800, v9
	v_lshlrev_b32_e32 v116, 1, v8
	v_readlane_b32 s95, v253, 23
	v_readlane_b32 s96, v253, 20
	s_mov_b32 s97, s84
	v_readlane_b32 s85, v254, 37
	global_load_dwordx4 v[208:211], v[104:105], off
	global_load_dwordx4 v[212:215], v[104:105], off offset:64
	global_load_dwordx4 v[216:219], v[104:105], off offset:128
	global_load_dwordx4 v[220:223], v[104:105], off offset:192
	s_branch .LBB0_335

; #define LAS __attribute__((address_space(3)))
; DI void hg_out_units(LAS unsigned char* L, int u0, int G, const float* LOGF, const bf16* QHG, const bf16* IHG, const bf16* GHG, const bf16* ST, const float* og, bf16* MIX, int tid, int wave, int lane) {
;     ...
;     for (;;) {
;     const int bh = unit >> 6, n = unit & 63, b_ = bh >> 3, h = bh & 7; const size_t tok0 = (size_t)b_ * SEQ + n * 64;
;     const bf16* stp = ST + (size_t)unit * 16384;
;     bf16x8 stf[4][4]; u32x2 gtv[4];
; #pragma unroll
;     for (int d = 0; d < 4; ++d) { const int dt = 4 * dh + d;
; #pragma unroll
;         for (int ks = 0; ks < 4; ++ks) stf[d][ks] = *(const bf16x8*)(stp + (size_t)(16 * dt + lr) * 128 + 32 * ks + quad * 8);
;         gtv[d] = *(const u32x2*)(GHG + (tok0 + 16 * tt + lr) * 1024 + h * 128 + 16 * dt + quad * 4); }
;     float tot = 0.f;
; #pragma unroll
;     for (int i = 0; i < 16; ++i) tot += g[i];
;     segtot[seg * 128 + c] = tot;
; #pragma unroll
;     for (int i = 0; i < 2; ++i) { const int cid = tid + 512 * i, kv = cid >> 4, dvs = (cid & 15) * 8; *(LAS bf16x8*)(Vs + kv * 160 + dvs) = v8[i]; }
;     __syncthreads();
.LBB0_335:
	s_ashr_i32 s86, s97, 9
	s_ashr_i32 s87, s86, 31
	s_lshl_b64 s[86:87], s[86:87], 12
	s_and_b32 s25, s96, 0xfc0
	s_or_b32 s86, s86, s25
	v_lshl_add_u64 v[126:127], s[86:87], 0, v[98:99]
	v_lshlrev_b64 v[8:9], 11, v[126:127]
	s_and_b32 s25, s95, 0x380
	v_lshl_add_u64 v[8:9], v[90:91], 0, v[8:9]
	s_lshl_b32 s36, s25, 1
	v_lshl_add_u64 v[8:9], v[8:9], 0, s[36:37]
	v_lshl_add_u64 v[72:73], v[8:9], 0, v[160:161]
	v_lshl_add_u64 v[230:231], v[108:109], 0, v[224:225]
	s_mov_b32 s98, 0x2000
	s_mov_b32 s99, 0
	s_mov_b32 m0, s100
	s_nop 0
	global_load_lds_dwordx4 v[230:231], off
	v_lshl_add_u64 v[230:231], v[230:231], 0, s[98:99]
	s_add_i32 m0, s100, 0x2000
	s_nop 0
	global_load_lds_dwordx4 v[230:231], off
	v_lshl_add_u64 v[230:231], v[230:231], 0, s[98:99]
	s_add_i32 m0, s100, 0x4000
	s_nop 0
	global_load_lds_dwordx4 v[230:231], off
	v_lshl_add_u64 v[230:231], v[230:231], 0, s[98:99]
	s_add_i32 m0, s100, 0x6000
	s_nop 0
	global_load_lds_dwordx4 v[230:231], off
	s_mov_b32 s81, s37
	v_lshl_add_u64 v[8:9], v[72:73], 0, s[80:81]
	global_load_dwordx2 v[124:125], v[8:9], off
	s_mov_b32 s25, s37
	v_lshl_add_u64 v[8:9], v[72:73], 0, s[24:25]
	global_load_dwordx2 v[122:123], v[8:9], off
	s_mov_b32 s69, s37
	v_lshl_add_u64 v[8:9], v[72:73], 0, s[68:69]
	global_load_dwordx2 v[120:121], v[8:9], off
	s_mov_b32 s75, s37
	v_lshl_add_u64 v[72:73], v[72:73], 0, s[74:75]
	global_load_dwordx2 v[118:119], v[72:73], off
	s_waitcnt vmcnt(41)
	v_add_f32_e32 v72, 0, v129
	s_waitcnt vmcnt(39)
	v_add_f32_e32 v72, v72, v131
	s_waitcnt vmcnt(37)
	v_add_f32_e32 v72, v72, v133
	s_waitcnt vmcnt(35)
	v_add_f32_e32 v72, v72, v135
	s_waitcnt vmcnt(33)
	v_add_f32_e32 v72, v72, v137
	s_waitcnt vmcnt(31)
	v_add_f32_e32 v72, v72, v139
	s_waitcnt vmcnt(29)
	v_add_f32_e32 v72, v72, v142
	s_waitcnt vmcnt(27)
	v_add_f32_e32 v72, v72, v148
	s_waitcnt vmcnt(25)
	v_add_f32_e32 v72, v72, v152
	s_waitcnt vmcnt(23)
	v_add_f32_e32 v72, v72, v154
	s_waitcnt vmcnt(21)
	v_add_f32_e32 v72, v72, v156
	s_waitcnt vmcnt(19)
	v_add_f32_e32 v72, v72, v173
	s_waitcnt vmcnt(17)
	v_add_f32_e32 v72, v72, v175
	s_waitcnt vmcnt(15)
	v_add_f32_e32 v72, v72, v177
	s_waitcnt vmcnt(13)
	v_add_f32_e32 v72, v72, v179
	v_mov_b32_e32 v73, 0
	s_waitcnt vmcnt(11)
	v_add_f32_e32 v72, v72, v181
	ds_write_b32 v141, v72
	s_waitcnt vmcnt(9)
	ds_write_b128 v101, v[0:3] offset:52224
	s_waitcnt vmcnt(8)
	ds_write_b128 v157, v[4:7] offset:52224
	s_waitcnt lgkmcnt(0)
	s_barrier
	s_and_saveexec_b64 s[86:87], s[6:7]
	s_cbranch_execz .LBB0_337
	ds_read_b32 v72, v143
	s_waitcnt lgkmcnt(0)
	v_add_f32_e32 v73, 0, v72

; #define LAS __attribute__((address_space(3)))
; DI unsigned pk2(float lo, float hi) { f32x2_t v = {lo, hi}; bf16x2_t b = __builtin_convertvector(v, bf16x2_t); return __builtin_bit_cast(unsigned, b); }
; DI void hg_out_units(LAS unsigned char* L, int u0, int G, const float* LOGF, const bf16* QHG, const bf16* IHG, const bf16* GHG, const bf16* ST, const float* og, bf16* MIX, int tid, int wave, int lane) {
;     ...
;         u32x2 w; w.x = pk2(acc[0], acc[1]); w.y = pk2(acc[2], acc[3]); *(LAS u32x2*)(At + (16 * tt + lr) * 72 + 16 * st + quad * 4) = w; }
;     __syncthreads();
.LBB0_349:
	v_cvt_pk_bf16_f32 v72, v72, v73
	v_cvt_pk_bf16_f32 v73, v74, v75
	v_add_u32_e32 v74, s94, v146
	ds_write_b64 v74, v[72:73]
	s_and_b64 vcc, exec, s[86:87]
	s_cbranch_vccnz .Lhgo_last
	s_waitcnt vmcnt(34)
	s_branch .Lhgo_go

; #define LAS __attribute__((address_space(3)))
; DI void hg_out_units(LAS unsigned char* L, int u0, int G, const float* LOGF, const bf16* QHG, const bf16* IHG, const bf16* GHG, const bf16* ST, const float* og, bf16* MIX, int tid, int wave, int lane) {
;     ...
;     pg8::f32x4 acc[4];
;     bf16x8 bA[2], bQ[4];
; #pragma unroll
;     for (int ks = 0; ks < 2; ++ks) bA[ks] = *(const LAS bf16x8*)(At + (16 * tt + lr) * 72 + 32 * ks + quad * 8);
; #pragma unroll
;     for (int ks = 0; ks < 4; ++ks) bQ[ks] = *(const LAS bf16x8*)(Qh + (16 * tt + lr) * 136 + 32 * ks + quad * 8);
;     float ss = 0.f;
; #pragma unroll
;     for (int d = 0; d < 4; ++d) { const int dt = 4 * dh + d; acc[d] = (pg8::f32x4){0.f, 0.f, 0.f, 0.f};
; #pragma unroll
;         for (int ks = 0; ks < 2; ++ks) { const LAS bf16* vp = Vs + (32 * ks + quad * 8 + (lr >> 2)) * 160 + 16 * dt + 4 * (lr & 3);
;             const s16x4 lo = __builtin_bit_cast(s16x4, __builtin_amdgcn_ds_read_tr16_b64_v4i16((LAS v4i16_t*)vp)), hi = __builtin_bit_cast(s16x4, __builtin_amdgcn_ds_read_tr16_b64_v4i16((LAS v4i16_t*)(vp + 4 * 160)));
;             const bf16x8 a = __builtin_shufflevector(lo, hi, 0, 1, 2, 3, 4, 5, 6, 7); acc[d] = __builtin_amdgcn_mfma_f32_16x16x32_bf16(a, bA[ks], acc[d], 0, 0, 0); }
; #pragma unroll
;         for (int ks = 0; ks < 4; ++ks) acc[d] = __builtin_amdgcn_mfma_f32_16x16x32_bf16(stf[d][ks], bQ[ks], acc[d], 0, 0, 0);
;         ss += (acc[d][0] * acc[d][0] + acc[d][1] * acc[d][1]) + (acc[d][2] * acc[d][2] + acc[d][3] * acc[d][3]); }
.Lhgo_go:
	s_waitcnt lgkmcnt(0)
	s_barrier
	ds_read_b128 v[68:71], v226
	ds_read_b128 v[52:55], v227
	ds_read_b128 v[48:51], v228
	ds_read_b128 v[44:47], v229
	ds_read_b128 v[56:59], v226 offset:4096
	ds_read_b128 v[60:63], v227 offset:4096
	ds_read_b128 v[64:67], v228 offset:4096
	ds_read_b128 v[32:35], v229 offset:4096
	ds_read_b128 v[36:39], v226 offset:8192
	ds_read_b128 v[40:43], v227 offset:8192
	ds_read_b128 v[28:31], v228 offset:8192
	ds_read_b128 v[24:27], v229 offset:8192
	ds_read_b128 v[20:23], v226 offset:12288
	ds_read_b128 v[16:19], v227 offset:12288
	ds_read_b128 v[12:15], v228 offset:12288
	ds_read_b128 v[8:11], v229 offset:12288
	ds_read_b64_tr_b16 v[74:75], v171 offset:53504
	ds_read_b64_tr_b16 v[72:73], v171 offset:52224
	v_add_u32_e32 v76, v145, v100
	ds_read_b128 v[80:83], v76
	ds_read_b64_tr_b16 v[184:185], v171 offset:62464
	ds_read_b64_tr_b16 v[186:187], v171 offset:63744
	ds_read_b128 v[76:79], v76 offset:64
	s_waitcnt lgkmcnt(3)
	v_mfma_f32_16x16x32_bf16 v[72:75], v[72:75], v[80:83], 0
	s_mov_b32 s25, -1
	s_waitcnt lgkmcnt(0)
	v_mfma_f32_16x16x32_bf16 v[184:187], v[184:187], v[76:79], v[72:75]
	s_nop 4
	ds_read_b128 v[72:75], v147 offset:34816
	ds_read_b64_tr_b16 v[188:189], v171 offset:52256
	ds_read_b64_tr_b16 v[190:191], v171 offset:53536
	s_waitcnt lgkmcnt(2)
	v_mfma_f32_16x16x32_bf16 v[184:187], v[68:71], v[72:75], v[184:187]
	ds_read_b128 v[68:71], v147 offset:34880
	s_waitcnt lgkmcnt(0)
	v_mfma_f32_16x16x32_bf16 v[184:187], v[52:55], v[68:71], v[184:187]
	ds_read_b128 v[52:55], v147 offset:34944
	s_waitcnt lgkmcnt(0)
	v_mfma_f32_16x16x32_bf16 v[184:187], v[48:51], v[52:55], v[184:187]
	ds_read_b128 v[48:51], v147 offset:35008
	ds_read_b64_tr_b16 v[192:193], v171 offset:62496
	ds_read_b64_tr_b16 v[194:195], v171 offset:63776
	v_mfma_f32_16x16x32_bf16 v[188:191], v[188:191], v[80:83], 0
	s_waitcnt lgkmcnt(2)
	v_mfma_f32_16x16x32_bf16 v[44:47], v[44:47], v[48:51], v[184:187]
	s_waitcnt lgkmcnt(0)
	v_mfma_f32_16x16x32_bf16 v[184:187], v[192:195], v[76:79], v[188:191]
	v_mfma_f32_16x16x32_bf16 v[56:59], v[56:59], v[72:75], v[184:187]
	v_mfma_f32_16x16x32_bf16 v[56:59], v[60:63], v[68:71], v[56:59]
	ds_read_b64_tr_b16 v[60:61], v171 offset:52288
	v_mfma_f32_16x16x32_bf16 v[56:59], v[64:67], v[52:55], v[56:59]
	v_mfma_f32_16x16x32_bf16 v[32:35], v[32:35], v[48:51], v[56:59]
	ds_read_b64_tr_b16 v[62:63], v171 offset:53568
	s_nop 4
	ds_read_b64_tr_b16 v[56:57], v171 offset:62528
	ds_read_b64_tr_b16 v[58:59], v171 offset:63808
	s_waitcnt lgkmcnt(2)
	v_mfma_f32_16x16x32_bf16 v[60:63], v[60:63], v[80:83], 0
	s_waitcnt lgkmcnt(0)
	v_mfma_f32_16x16x32_bf16 v[56:59], v[56:59], v[76:79], v[60:63]
	v_mfma_f32_16x16x32_bf16 v[36:39], v[36:39], v[72:75], v[56:59]
	v_mfma_f32_16x16x32_bf16 v[36:39], v[40:43], v[68:71], v[36:39]
	ds_read_b64_tr_b16 v[40:41], v171 offset:52320
	s_nop 2
	v_mul_f32_e32 v56, v45, v45
	v_fmac_f32_e32 v56, v44, v44
	v_mfma_f32_16x16x32_bf16 v[28:31], v[28:31], v[52:55], v[36:39]
	ds_read_b64_tr_b16 v[42:43], v171 offset:53600
	s_nop 1
	ds_read_b64_tr_b16 v[36:37], v171 offset:62560
	ds_read_b64_tr_b16 v[38:39], v171 offset:63840
	v_mfma_f32_16x16x32_bf16 v[24:27], v[24:27], v[48:51], v[28:31]
	s_waitcnt lgkmcnt(2)
	v_mfma_f32_16x16x32_bf16 v[28:31], v[40:43], v[80:83], 0
	v_mul_f32_e32 v40, v47, v47
	v_fmac_f32_e32 v40, v46, v46
	v_add_f32_e32 v40, v56, v40
	s_waitcnt lgkmcnt(0)
	v_mfma_f32_16x16x32_bf16 v[28:31], v[36:39], v[76:79], v[28:31]
	v_mul_f32_e32 v36, v33, v33
	v_mul_f32_e32 v37, v35, v35
	v_fmac_f32_e32 v36, v32, v32
	v_mfma_f32_16x16x32_bf16 v[20:23], v[20:23], v[72:75], v[28:31]
	v_fmac_f32_e32 v37, v34, v34
	v_mfma_f32_16x16x32_bf16 v[16:19], v[16:19], v[68:71], v[20:23]
	v_add_f32_e32 v28, v36, v37
	v_add_f32_e32 v28, v40, v28
	v_mfma_f32_16x16x32_bf16 v[12:15], v[12:15], v[52:55], v[16:19]
	s_nop 0
	v_mul_f32_e32 v20, v25, v25
	v_mul_f32_e32 v21, v27, v27
	v_fmac_f32_e32 v20, v24, v24
	v_mfma_f32_16x16x32_bf16 v[8:11], v[8:11], v[48:51], v[12:15]
	v_fmac_f32_e32 v21, v26, v26
	v_add_f32_e32 v16, v20, v21
	v_add_f32_e32 v16, v28, v16
	s_nop 4
	v_mul_f32_e32 v12, v9, v9
	v_mul_f32_e32 v13, v11, v11
	v_fmac_f32_e32 v12, v8, v8
	v_fmac_f32_e32 v13, v10, v10
	v_add_f32_e32 v12, v12, v13
	v_mbcnt_lo_u32_b32 v13, s25, 0
	v_mbcnt_hi_u32_b32 v13, s25, v13
	v_lshlrev_b32_e32 v13, 2, v13
	v_add_f32_e32 v12, v16, v12
	v_xor_b32_e32 v13, 64, v13
	ds_bpermute_b32 v13, v13, v12
	s_mov_b32 s25, -1
	s_waitcnt lgkmcnt(0)
	v_add_f32_e32 v12, v12, v13
	v_mbcnt_lo_u32_b32 v13, s25, 0
	v_mbcnt_hi_u32_b32 v13, s25, v13
	v_lshlrev_b32_e32 v13, 2, v13
	v_xor_b32_e32 v13, 0x80, v13
	ds_bpermute_b32 v13, v13, v12
	s_and_saveexec_b64 vcc, s[4:5]
	s_cbranch_execz .LBB0_334
	s_waitcnt lgkmcnt(0)
	v_add_f32_e32 v12, v12, v13
	ds_write_b32 v149, v12
	s_branch .LBB0_334
